# S5 GLU compact loops, padded so downstream code keeps its addresses
# speedup vs baseline: 1.0029x; 1.0029x over previous
; __device__ __forceinline__ float bf2f(unsigned short h) { return __uint_as_float(((unsigned)h) << 16); }
; __device__ __forceinline__ unsigned short f2bf(float f) { return (unsigned short)(cvt_pk(f, 0.f) & 0xffffu); }
; __device__ __forceinline__ float sigmoidf_(float x) { return fast_rcp(1.f + fast_exp2(-x * LOG2E)); }
; __device__ __forceinline__ void s5_unit(ArgsP A, int l, int unit, unsigned char* lds, int wave_, int lane_) {
;     ...
;     {
;         const bf16_t* wb = WG + (size_t)(64 * wave + (lane & 15)) * 512 + 8 * (lane >> 4);
;         bf16x8 bq[4][4];
; #pragma unroll
;         for (int p = 0; p < 4; ++p)
; #pragma unroll
;             for (int nb = 0; nb < 4; ++nb) bq[p][nb] = *(const bf16x8*)(wb + (size_t)(16 * nb) * 512 + 32 * p);
; #pragma unroll
;         for (int ks = 0; ks < 16; ++ks) {
;             bf16x8 af[4];
; #pragma unroll
;             for (int mb = 0; mb < 4; ++mb) af[mb] = *(const bf16x8*)(ys + (16 * mb + (lane & 15)) * YS_STRIDE + 32 * ks + 8 * (lane >> 4));
;             asm volatile("" : "+v"(bq[ks & 3][0]), "+v"(bq[ks & 3][1]), "+v"(bq[ks & 3][2]), "+v"(bq[ks & 3][3]) :: "memory");
; #pragma unroll
;             for (int mb = 0; mb < 4; ++mb)
; #pragma unroll
;                 for (int nb = 0; nb < 4; ++nb) acc[mb][nb] = __builtin_amdgcn_mfma_f32_16x16x32_bf16(af[mb], bq[ks & 3][nb], acc[mb][nb], 0, 0, 0);
;             if (ks + 4 < 16) {
; #pragma unroll
;                 for (int nb = 0; nb < 4; ++nb) bq[ks & 3][nb] = *(const bf16x8*)(wb + (size_t)(16 * nb) * 512 + 32 * (ks + 4));
;             }
;         }
;     }
;     bf16_t* MIX = (bf16_t*)(A->ws + WS_MIX);
;     float bglv[4];
; #pragma unroll
;     for (int nb = 0; nb < 4; ++nb) bglv[nb] = A->in[22][l * 512 + 64 * wave + 16 * nb + (lane & 15)];
; #pragma unroll
;     for (int nb = 0; nb < 4; ++nb) { const int n = 64 * wave + 16 * nb + (lane & 15); const float bgl = bglv[nb];
; #pragma unroll
;         for (int mb = 0; mb < 4; ++mb)
; #pragma unroll
;             for (int i = 0; i < 4; ++i) { const int t = 16 * mb + 4 * (lane >> 4) + i; const float yv = bf2f(ys[t * YS_STRIDE + n]);
;                 MIX[(size_t)(rowbase + t) * DM + n] = f2bf(yv * sigmoidf_(acc[mb][nb][i] + bgl)); } }
.Ls5g_k1:
	ds_read_b128 v[48:51], v146 offset:64
	ds_read_b128 v[52:55], v146 offset:16704
	ds_read_b128 v[56:59], v146 offset:33344
	ds_read_b128 v[60:63], v146 offset:49984
	s_waitcnt vmcnt(3) lgkmcnt(4)
	v_mfma_f32_16x16x32_bf16 v[0:3], v[16:19], v[32:35], v[0:3]
	v_mfma_f32_16x16x32_bf16 v[4:7], v[16:19], v[36:39], v[4:7]
	v_mfma_f32_16x16x32_bf16 v[8:11], v[16:19], v[40:43], v[8:11]
	v_mfma_f32_16x16x32_bf16 v[12:15], v[16:19], v[44:47], v[12:15]
	global_load_dwordx4 v[16:19], v145, s[6:7] offset:256
	ds_read_b128 v[32:35], v146 offset:128
	ds_read_b128 v[36:39], v146 offset:16768
	ds_read_b128 v[40:43], v146 offset:33408
	ds_read_b128 v[44:47], v146 offset:50048
	s_waitcnt vmcnt(3) lgkmcnt(4)
	v_mfma_f32_16x16x32_bf16 v[0:3], v[20:23], v[48:51], v[0:3]
	v_mfma_f32_16x16x32_bf16 v[4:7], v[20:23], v[52:55], v[4:7]
	v_mfma_f32_16x16x32_bf16 v[8:11], v[20:23], v[56:59], v[8:11]
	v_mfma_f32_16x16x32_bf16 v[12:15], v[20:23], v[60:63], v[12:15]
	global_load_dwordx4 v[20:23], v145, s[6:7] offset:320
	ds_read_b128 v[48:51], v146 offset:192
	ds_read_b128 v[52:55], v146 offset:16832
	ds_read_b128 v[56:59], v146 offset:33472
	ds_read_b128 v[60:63], v146 offset:50112
	s_waitcnt vmcnt(3) lgkmcnt(4)
	v_mfma_f32_16x16x32_bf16 v[0:3], v[24:27], v[32:35], v[0:3]
	v_mfma_f32_16x16x32_bf16 v[4:7], v[24:27], v[36:39], v[4:7]
	v_mfma_f32_16x16x32_bf16 v[8:11], v[24:27], v[40:43], v[8:11]
	v_mfma_f32_16x16x32_bf16 v[12:15], v[24:27], v[44:47], v[12:15]
	global_load_dwordx4 v[24:27], v145, s[6:7] offset:384
	ds_read_b128 v[32:35], v147
	ds_read_b128 v[36:39], v147 offset:16640
	ds_read_b128 v[40:43], v147 offset:33280
	ds_read_b128 v[44:47], v147 offset:49920
	s_waitcnt vmcnt(3) lgkmcnt(4)
	v_mfma_f32_16x16x32_bf16 v[0:3], v[28:31], v[48:51], v[0:3]
	v_mfma_f32_16x16x32_bf16 v[4:7], v[28:31], v[52:55], v[4:7]
	v_mfma_f32_16x16x32_bf16 v[8:11], v[28:31], v[56:59], v[8:11]
	v_mfma_f32_16x16x32_bf16 v[12:15], v[28:31], v[60:63], v[12:15]
	global_load_dwordx4 v[28:31], v145, s[6:7] offset:448
	v_add_u32_e32 v145, 0x100, v145
	v_add_u32_e32 v146, 0x100, v146
	v_add_u32_e32 v147, 0x100, v147
	s_add_i32 s5, s5, 1
	s_cmp_lt_u32 s5, 4
	s_cbranch_scc1 .Ls5g_k
	ds_read_b64 v[64:65], v149
	ds_read_b64 v[66:67], v149 offset:16640
	ds_read_b64 v[68:69], v149 offset:33280
	ds_read_b64 v[70:71], v149 offset:49920
	s_nop 7
	s_waitcnt vmcnt(4) lgkmcnt(0)
	v_add_f32_e32 v76, v0, v72
	v_add_f32_e32 v77, v1, v73
	v_add_f32_e32 v78, v2, v74
	v_add_f32_e32 v79, v3, v75
	v_mul_f32_e32 v76, 0xbfb8aa3b, v76
	v_mul_f32_e32 v77, 0xbfb8aa3b, v77
	v_mul_f32_e32 v78, 0xbfb8aa3b, v78
	v_mul_f32_e32 v79, 0xbfb8aa3b, v79
	v_exp_f32_e32 v76, v76
	v_exp_f32_e32 v77, v77
	v_exp_f32_e32 v78, v78
	v_exp_f32_e32 v79, v79
	v_lshlrev_b32_e32 v80, 16, v64
	v_and_b32_e32 v81, 0xffff0000, v64
	v_add_f32_e32 v76, 1.0, v76
	v_add_f32_e32 v77, 1.0, v77
	v_add_f32_e32 v78, 1.0, v78
	v_add_f32_e32 v79, 1.0, v79
	v_lshlrev_b32_e32 v82, 16, v65
	v_and_b32_e32 v83, 0xffff0000, v65
	v_rcp_f32_e32 v76, v76
	v_rcp_f32_e32 v77, v77
	v_rcp_f32_e32 v78, v78
	v_rcp_f32_e32 v79, v79
	s_nop 0
	v_mul_f32_e32 v80, v80, v76
	v_mul_f32_e32 v81, v81, v77
	v_mul_f32_e32 v82, v82, v78
	v_mul_f32_e32 v83, v83, v79
	v_cvt_pk_bf16_f32 v84, v80, v81
	v_cvt_pk_bf16_f32 v85, v82, v83
	ds_write_b64 v152, v[84:85]
	v_add_f32_e32 v76, v4, v72
	v_add_f32_e32 v77, v5, v73
	v_add_f32_e32 v78, v6, v74
	v_add_f32_e32 v79, v7, v75
	v_mul_f32_e32 v76, 0xbfb8aa3b, v76
	v_mul_f32_e32 v77, 0xbfb8aa3b, v77
	v_mul_f32_e32 v78, 0xbfb8aa3b, v78
	v_mul_f32_e32 v79, 0xbfb8aa3b, v79
	v_exp_f32_e32 v76, v76
	v_exp_f32_e32 v77, v77
	v_exp_f32_e32 v78, v78
	v_exp_f32_e32 v79, v79
	v_lshlrev_b32_e32 v80, 16, v66
	v_and_b32_e32 v81, 0xffff0000, v66
	v_add_f32_e32 v76, 1.0, v76
	v_add_f32_e32 v77, 1.0, v77
	v_add_f32_e32 v78, 1.0, v78
	v_add_f32_e32 v79, 1.0, v79
	v_lshlrev_b32_e32 v82, 16, v67
	v_and_b32_e32 v83, 0xffff0000, v67
	v_rcp_f32_e32 v76, v76
	v_rcp_f32_e32 v77, v77
	v_rcp_f32_e32 v78, v78
	v_rcp_f32_e32 v79, v79
	s_nop 0
	v_mul_f32_e32 v80, v80, v76
	v_mul_f32_e32 v81, v81, v77
	v_mul_f32_e32 v82, v82, v78
	v_mul_f32_e32 v83, v83, v79
	v_cvt_pk_bf16_f32 v84, v80, v81
	v_cvt_pk_bf16_f32 v85, v82, v83
	ds_write_b64 v152, v[84:85] offset:2304
	v_add_f32_e32 v76, v8, v72
	v_add_f32_e32 v77, v9, v73
	v_add_f32_e32 v78, v10, v74
	v_add_f32_e32 v79, v11, v75
	v_mul_f32_e32 v76, 0xbfb8aa3b, v76
	v_mul_f32_e32 v77, 0xbfb8aa3b, v77
	v_mul_f32_e32 v78, 0xbfb8aa3b, v78
	v_mul_f32_e32 v79, 0xbfb8aa3b, v79
	v_exp_f32_e32 v76, v76
	v_exp_f32_e32 v77, v77
	v_exp_f32_e32 v78, v78
	v_exp_f32_e32 v79, v79
	v_lshlrev_b32_e32 v80, 16, v68
	v_and_b32_e32 v81, 0xffff0000, v68
	v_add_f32_e32 v76, 1.0, v76
	v_add_f32_e32 v77, 1.0, v77
	v_add_f32_e32 v78, 1.0, v78
	v_add_f32_e32 v79, 1.0, v79
	v_lshlrev_b32_e32 v82, 16, v69
	v_and_b32_e32 v83, 0xffff0000, v69
	v_rcp_f32_e32 v76, v76
	v_rcp_f32_e32 v77, v77
	v_rcp_f32_e32 v78, v78
	v_rcp_f32_e32 v79, v79
	s_nop 0
	v_mul_f32_e32 v80, v80, v76
	v_mul_f32_e32 v81, v81, v77
	v_mul_f32_e32 v82, v82, v78
	v_mul_f32_e32 v83, v83, v79
	v_cvt_pk_bf16_f32 v84, v80, v81
	v_cvt_pk_bf16_f32 v85, v82, v83
	ds_write_b64 v152, v[84:85] offset:4608
	v_add_f32_e32 v76, v12, v72
	v_add_f32_e32 v77, v13, v73
	v_add_f32_e32 v78, v14, v74
	v_add_f32_e32 v79, v15, v75
	v_mul_f32_e32 v76, 0xbfb8aa3b, v76
	v_mul_f32_e32 v77, 0xbfb8aa3b, v77
	v_mul_f32_e32 v78, 0xbfb8aa3b, v78
	v_mul_f32_e32 v79, 0xbfb8aa3b, v79
	v_exp_f32_e32 v76, v76
	v_exp_f32_e32 v77, v77
	v_exp_f32_e32 v78, v78
	v_exp_f32_e32 v79, v79
	v_lshlrev_b32_e32 v80, 16, v70
	v_and_b32_e32 v81, 0xffff0000, v70
	v_add_f32_e32 v76, 1.0, v76
	v_add_f32_e32 v77, 1.0, v77
	v_add_f32_e32 v78, 1.0, v78
	v_add_f32_e32 v79, 1.0, v79
	v_lshlrev_b32_e32 v82, 16, v71
	v_and_b32_e32 v83, 0xffff0000, v71
	v_rcp_f32_e32 v76, v76
	v_rcp_f32_e32 v77, v77
	v_rcp_f32_e32 v78, v78
	v_rcp_f32_e32 v79, v79
	s_nop 0
	v_mul_f32_e32 v80, v80, v76
	v_mul_f32_e32 v81, v81, v77
	v_mul_f32_e32 v82, v82, v78
	v_mul_f32_e32 v83, v83, v79
	v_cvt_pk_bf16_f32 v84, v80, v81
	v_cvt_pk_bf16_f32 v85, v82, v83
	ds_write_b64 v152, v[84:85] offset:6912
	v_add_u32_e32 v144, 0x4000, v144
	v_add_u32_e32 v149, 32, v149
	v_add_u32_e32 v152, 32, v152
	v_add_u32_e32 v156, 64, v156
	s_add_i32 s4, s4, 1
	s_cmp_lt_u32 s4, 4
	s_cbranch_scc1 .Ls5g_nb
; __device__ __forceinline__ float bf2f(unsigned short h) { return __uint_as_float(((unsigned)h) << 16); }
; __device__ __forceinline__ unsigned short f2bf(float f) { return (unsigned short)(cvt_pk(f, 0.f) & 0xffffu); }
; __device__ __forceinline__ float sigmoidf_(float x) { return fast_rcp(1.f + fast_exp2(-x * LOG2E)); }
; __device__ __forceinline__ void s5_unit(ArgsP A, int l, int unit, unsigned char* lds, int wave_, int lane_) {
;     ...
;     for (int nb = 0; nb < 4; ++nb) { const int n = 64 * wave + 16 * nb + (lane & 15); const float bgl = bglv[nb];
; #pragma unroll
;         for (int mb = 0; mb < 4; ++mb)
; #pragma unroll
;             for (int i = 0; i < 4; ++i) { const int t = 16 * mb + 4 * (lane >> 4) + i; const float yv = bf2f(ys[t * YS_STRIDE + n]);
;                 MIX[(size_t)(rowbase + t) * DM + n] = f2bf(yv * sigmoidf_(acc[mb][nb][i] + bgl)); } }
;     __syncthreads();
	s_waitcnt lgkmcnt(0)
	s_add_u32 s4, s2, 0x24f90000
	s_addc_u32 s5, s3, 0
	ds_read_b128 v[64:67], v155
	ds_read_b128 v[68:71], v155 offset:1152
	ds_read_b128 v[72:75], v155 offset:2304
	ds_read_b128 v[76:79], v155 offset:3456
	ds_read_b128 v[80:83], v155 offset:4608
	ds_read_b128 v[84:87], v155 offset:5760
	ds_read_b128 v[88:91], v155 offset:6912
	ds_read_b128 v[92:95], v155 offset:8064
	v_add_u32_e32 v158, 0x8000, v157
	v_add_u32_e32 v159, 0x8000, v158
	v_add_u32_e32 v160, 0x8000, v159
	v_add_u32_e32 v161, 0x8000, v160
	v_add_u32_e32 v162, 0x8000, v161
	v_add_u32_e32 v163, 0x8000, v162
	v_add_u32_e32 v164, 0x8000, v163
	s_waitcnt lgkmcnt(7)
	global_store_dwordx4 v157, v[64:67], s[4:5]
	s_waitcnt lgkmcnt(6)
	global_store_dwordx4 v158, v[68:71], s[4:5]
	s_waitcnt lgkmcnt(5)
	global_store_dwordx4 v159, v[72:75], s[4:5]
	s_waitcnt lgkmcnt(4)
	global_store_dwordx4 v160, v[76:79], s[4:5]
	s_waitcnt lgkmcnt(3)
	global_store_dwordx4 v161, v[80:83], s[4:5]
	s_waitcnt lgkmcnt(2)
	global_store_dwordx4 v162, v[84:87], s[4:5]
	s_waitcnt lgkmcnt(1)
	global_store_dwordx4 v163, v[88:91], s[4:5]
	s_waitcnt lgkmcnt(0)
	global_store_dwordx4 v164, v[92:95], s[4:5]
	s_waitcnt vmcnt(8)
	s_mov_b64 s[2:3], 0
	s_barrier
	s_branch .LBB0_785
	s_nop 0
	s_nop 0
	s_nop 0
	s_nop 0
	s_nop 0
	s_nop 0
	s_nop 0
	s_nop 0
	s_nop 0
	s_nop 0
	s_nop 0
	s_nop 0
	s_nop 0
	s_nop 0
	s_nop 0
	s_nop 0
	s_nop 0
	s_nop 0
	s_nop 0
	s_nop 0
	s_nop 0
	s_nop 0
	s_nop 0
	s_nop 0
	s_nop 0
	s_nop 0
	s_nop 0
	s_nop 0
	s_nop 0
	s_nop 0
	s_nop 0
	s_nop 0
	s_nop 0
	s_nop 0
	s_nop 0
	s_nop 0
	s_nop 0
	s_nop 0
	s_nop 0
	s_nop 0
	s_nop 0
	s_nop 0
	s_nop 0
	s_nop 0
	s_nop 0
	s_nop 0
	s_nop 0
	s_nop 0
	s_nop 0
	s_nop 0
	s_nop 0
	s_nop 0
	s_nop 0
	s_nop 0
	s_nop 0
	s_nop 0
	s_nop 0
	s_nop 0
	s_nop 0
	s_nop 0
	s_nop 0
	s_nop 0
	s_nop 0
	s_nop 0
	s_nop 0
	s_nop 0
	s_nop 0
	s_nop 0
	s_nop 0
	s_nop 0
	s_nop 0
	s_nop 0
	s_nop 0
	s_nop 0
	s_nop 0
	s_nop 0
	s_nop 0
	s_nop 0
	s_nop 0
	s_nop 0
	s_nop 0
	s_nop 0
	s_nop 0
	s_nop 0
	s_nop 0
	s_nop 0
	s_nop 0
	s_nop 0
	s_nop 0
	s_nop 0
	s_nop 0
	s_nop 0
	s_nop 0
	s_nop 0
	s_nop 0
	s_nop 0
	s_nop 0
	s_nop 0
	s_nop 0
	s_nop 0
	s_nop 0
	s_nop 0
	s_nop 0
	s_nop 0
	s_nop 0
	s_nop 0
	s_nop 0
	s_nop 0
	s_nop 0
	s_nop 0
	s_nop 0
	s_nop 0
	s_nop 0
	s_nop 0
	s_nop 0
	s_nop 0
	s_nop 0
	s_nop 0
	s_nop 0
	s_nop 0
	s_nop 0
	s_nop 0
	s_nop 0
	s_nop 0
	s_nop 0
	s_nop 0
	s_nop 0
	s_nop 0
	s_nop 0
	s_nop 0
	s_nop 0
	s_nop 0
	s_nop 0
	s_nop 0
	s_nop 0
	s_nop 0
	s_nop 0
	s_nop 0
	s_nop 0
	s_nop 0
	s_nop 0
	s_nop 0
	s_nop 0
	s_nop 0
	s_nop 0
	s_nop 0
	s_nop 0
	s_nop 0
	s_nop 0
	s_nop 0
	s_nop 0
	s_nop 0
	s_nop 0
	s_nop 0
	s_nop 0
	s_nop 0
	s_nop 0
	s_nop 0
	s_nop 0
	s_nop 0
	s_nop 0
	s_nop 0
	s_nop 0
	s_nop 0
	s_nop 0
	s_nop 0
	s_nop 0
	s_nop 0
	s_nop 0
	s_nop 0
	s_nop 0
	s_nop 0
	s_nop 0
	s_nop 0
	s_nop 0
	s_nop 0
	s_nop 0
	s_nop 0
	s_nop 0
	s_nop 0
	s_nop 0
	s_nop 0
	s_nop 0
	s_nop 0
	s_nop 0
	s_nop 0
	s_nop 0
	s_nop 0
	s_nop 0
	s_nop 0
	s_nop 0
	s_nop 0
	s_nop 0
	s_nop 0
	s_nop 0
	s_nop 0
	s_nop 0
	s_nop 0
	s_nop 0
	s_nop 0
	s_nop 0
	s_nop 0
	s_nop 0
	s_nop 0
	s_nop 0
	s_nop 0
	s_nop 0
	s_nop 0
	s_nop 0
	s_nop 0
	s_nop 0
	s_nop 0
	s_nop 0
	s_nop 0
	s_nop 0
	s_nop 0
	s_nop 0
	s_nop 0
	s_nop 0
	s_nop 0
	s_nop 0
	s_nop 0
	s_nop 0
	s_nop 0
	s_nop 0
	s_nop 0
	s_nop 0
	s_nop 0
	s_nop 0
	s_nop 0
	s_nop 0
	s_nop 0
	s_nop 0
	s_nop 0
	s_nop 0
	s_nop 0
	s_nop 0
	s_nop 0
	s_nop 0
	s_nop 0
	s_nop 0
	s_nop 0
	s_nop 0
	s_nop 0
	s_nop 0
	s_nop 0
	s_nop 0
	s_nop 0
	s_nop 0
	s_nop 0
	s_nop 0
	s_nop 0
	s_nop 0
	s_nop 0
	s_nop 0
	s_nop 0
	s_nop 0
	s_nop 0
	s_nop 0
	s_nop 0
	s_nop 0
	s_nop 0
	s_nop 0
	s_nop 0
	s_nop 0
	s_nop 0
	s_nop 0
	s_nop 0
	s_nop 0
	s_nop 0
	s_nop 0
	s_nop 0
	s_nop 0
	s_nop 0
	s_nop 0
	s_nop 0
	s_nop 0
	s_nop 0
	s_nop 0
	s_nop 0
	s_nop 0
	s_nop 0
	s_nop 0
	s_nop 0
	s_nop 0
	s_nop 0
	s_nop 0
	s_nop 0
	s_nop 0
	s_nop 0
	s_nop 0
	s_nop 0
	s_nop 0
	s_nop 0
	s_nop 0
	s_nop 0
	s_nop 0
	s_nop 0
	s_nop 0
	s_nop 0
	s_nop 0
	s_nop 0
	s_nop 0
	s_nop 0
	s_nop 0
	s_nop 0
	s_nop 0
	s_nop 0
	s_nop 0
	s_nop 0
	s_nop 0
	s_nop 0
	s_nop 0
	s_nop 0
	s_nop 0
	s_nop 0
	s_nop 0
	s_nop 0
	s_nop 0
	s_nop 0
	s_nop 0
	s_nop 0
	s_nop 0
	s_nop 0
	s_nop 0
	s_nop 0
	s_nop 0
	s_nop 0
	s_nop 0
	s_nop 0
	s_nop 0
	s_nop 0
	s_nop 0
	s_nop 0
	s_nop 0
	s_nop 0
	s_nop 0
	s_nop 0
	s_nop 0
	s_nop 0
	s_nop 0
	s_nop 0
	s_nop 0
	s_nop 0
	s_nop 0
	s_nop 0
	s_nop 0
	s_nop 0
	s_nop 0
	s_nop 0
	s_nop 0
	s_nop 0
	s_nop 0
	s_nop 0
	s_nop 0
	s_nop 0
	s_nop 0
	s_nop 0
	s_nop 0
	s_nop 0
	s_nop 0
	s_nop 0
	s_nop 0
	s_nop 0
	s_nop 0
	s_nop 0
	s_nop 0
	s_nop 0
	s_nop 0
	s_nop 0
	s_nop 0
	s_nop 0
	s_nop 0
	s_nop 0
	s_nop 0
	s_nop 0
	s_nop 0
	s_nop 0
	s_nop 0
	s_nop 0
	s_nop 0
	s_nop 0
	s_nop 0
	s_nop 0
	s_nop 0
	s_nop 0
	s_nop 0
	s_nop 0
	s_nop 0
	s_nop 0
	s_nop 0
	s_nop 0
	s_nop 0
	s_nop 0
	s_nop 0
	s_nop 0
	s_nop 0
	s_nop 0
	s_nop 0
	s_nop 0
	s_nop 0
	s_nop 0
	s_nop 0
	s_nop 0
	s_nop 0
	s_nop 0
	s_nop 0
	s_nop 0
	s_nop 0
	s_nop 0
	s_nop 0
	s_nop 0
	s_nop 0
	s_nop 0
	s_nop 0
	s_nop 0
	s_nop 0
	s_nop 0
	s_nop 0
	s_nop 0
	s_nop 0
	s_nop 0
	s_nop 0
	s_nop 0
	s_nop 0
	s_nop 0
	s_nop 0
	s_nop 0
	s_nop 0
	s_nop 0
	s_nop 0
	s_nop 0
	s_nop 0
	s_nop 0
	s_nop 0
	s_nop 0
	s_nop 0
	s_nop 0
	s_nop 0
	s_nop 0
	s_nop 0
	s_nop 0
	s_nop 0
	s_nop 0
	s_nop 0
	s_nop 0
	s_nop 0
	s_nop 0
	s_nop 0
	s_nop 0
	s_nop 0
	s_nop 0
	s_nop 0
	s_nop 0
	s_nop 0
	s_nop 0
	s_nop 0
	s_nop 0
	s_nop 0
	s_nop 0
	s_nop 0
	s_nop 0
	s_nop 0
	s_nop 0
	s_nop 0
	s_nop 0
	s_nop 0
	s_nop 0
	s_nop 0
	s_nop 0
	s_nop 0
	s_nop 0
	s_nop 0
	s_nop 0
	s_nop 0
	s_nop 0
	s_nop 0
	s_nop 0
	s_nop 0
	s_nop 0
	s_nop 0
	s_nop 0
	s_nop 0
	s_nop 0
	s_nop 0
	s_nop 0
	s_nop 0
	s_nop 0
	s_nop 0
; __device__ __forceinline__ float bf2f(unsigned short h) { return __uint_as_float(((unsigned)h) << 16); }
; __device__ __forceinline__ void s5_unit(ArgsP A, int l, int unit, unsigned char* lds, int wave_, int lane_) {
;     ...
;     __syncthreads();
;     const bf16_t* WG = (const bf16_t*)(A->ws + WS_W + (size_t)l * WL_SIZE + WL_WGLU);
;     f32x4 acc[4][4];
; #pragma unroll
;     for (int mb = 0; mb < 4; ++mb)
; #pragma unroll
;         for (int nb = 0; nb < 4; ++nb) acc[mb][nb] = (f32x4){0.f, 0.f, 0.f, 0.f};
;     {
;         const bf16_t* wb = WG + (size_t)(64 * wave + (lane & 15)) * 512 + 8 * (lane >> 4);
;         bf16x8 bq[4][4];
; #pragma unroll
;         for (int p = 0; p < 4; ++p)
; #pragma unroll
;             for (int nb = 0; nb < 4; ++nb) bq[p][nb] = *(const bf16x8*)(wb + (size_t)(16 * nb) * 512 + 32 * p);
; #pragma unroll
;         for (int ks = 0; ks < 16; ++ks) {
;             bf16x8 af[4];
; #pragma unroll
;             for (int mb = 0; mb < 4; ++mb) af[mb] = *(const bf16x8*)(ys + (16 * mb + (lane & 15)) * YS_STRIDE + 32 * ks + 8 * (lane >> 4));
;             asm volatile("" : "+v"(bq[ks & 3][0]), "+v"(bq[ks & 3][1]), "+v"(bq[ks & 3][2]), "+v"(bq[ks & 3][3]) :: "memory");
; #pragma unroll
;             for (int mb = 0; mb < 4; ++mb)
; #pragma unroll
;                 for (int nb = 0; nb < 4; ++nb) acc[mb][nb] = __builtin_amdgcn_mfma_f32_16x16x32_bf16(af[mb], bq[ks & 3][nb], acc[mb][nb], 0, 0, 0);
;             if (ks + 4 < 16) {
; #pragma unroll
;                 for (int nb = 0; nb < 4; ++nb) bq[ks & 3][nb] = *(const bf16x8*)(wb + (size_t)(16 * nb) * 512 + 32 * (ks + 4));
;             }
;         }
;     }
;     bf16_t* MIX = (bf16_t*)(A->ws + WS_MIX);
;     float bglv[4];
; #pragma unroll
;     for (int nb = 0; nb < 4; ++nb) bglv[nb] = A->in[22][l * 512 + 64 * wave + 16 * nb + (lane & 15)];
; #pragma unroll
;     for (int nb = 0; nb < 4; ++nb) { const int n = 64 * wave + 16 * nb + (lane & 15); const float bgl = bglv[nb];
; #pragma unroll
;         for (int mb = 0; mb < 4; ++mb)
; #pragma unroll
;             for (int i = 0; i < 4; ++i) { const int t = 16 * mb + 4 * (lane >> 4) + i; const float yv = bf2f(ys[t * YS_STRIDE + n]);
;                 MIX[(size_t)(rowbase + t) * DM + n] = f2bf(yv * sigmoidf_(acc[mb][nb][i] + bgl)); } }
;     __syncthreads();
	s_nop 0
	s_nop 0
	s_nop 0
	s_nop 0
	s_nop 0
	s_nop 0
	s_nop 0
	s_nop 0
	s_nop 0
	s_nop 0
	s_nop 0
	s_nop 0
	s_nop 0
	s_nop 0
	s_nop 0
	s_nop 0
	s_nop 0
	s_nop 0
	s_nop 0
	s_nop 0
	s_nop 0
	s_nop 0
	s_nop 0
	s_nop 0
	s_nop 0
	s_nop 0
	s_nop 0
	s_nop 0
	s_nop 0
	s_nop 0
	s_nop 0
	s_nop 0
	s_nop 0
	s_nop 0
	s_nop 0
	s_nop 0
	s_nop 0
	s_nop 0
	s_nop 0
	s_nop 0
	s_nop 0
	s_nop 0
	s_nop 0
	s_nop 0
	s_nop 0
	s_nop 0
	s_nop 0
	s_nop 0
	s_nop 0
	s_nop 0
	s_nop 0
	s_nop 0
	s_nop 0
	s_nop 0
	s_nop 0
	s_nop 0
	s_nop 0
	s_nop 0
	s_nop 0
	s_nop 0
	s_nop 0
	s_nop 0
	s_nop 0
	s_nop 0
	s_nop 0
	s_nop 0
	s_nop 0
	s_nop 0
	s_nop 0
	s_nop 0
	s_nop 0
	s_nop 0
	s_nop 0
	s_nop 0
	s_nop 0
	s_nop 0
	s_nop 0
	s_nop 0
	s_nop 0
	s_nop 0
	s_nop 0
	s_nop 0
	s_nop 0
	s_nop 0
	s_nop 0
	s_nop 0
	s_nop 0
	s_nop 0
	s_nop 0
	s_nop 0
	s_nop 0
	s_nop 0
	s_nop 0
	s_nop 0
	s_nop 0
	s_nop 0
	s_nop 0
	s_nop 0
	s_nop 0
	s_nop 0
	s_nop 0
	s_nop 0
	s_nop 0
	s_nop 0
	s_nop 0
	s_nop 0
	s_nop 0
	s_nop 0
	s_nop 0
	s_nop 0
	s_nop 0
	s_nop 0
	s_nop 0
	s_nop 0
	s_nop 0
	s_nop 0
	s_nop 0
	s_nop 0
	s_nop 0
	s_nop 0
	s_nop 0
	s_nop 0
	s_nop 0
	s_nop 0
	s_nop 0
	s_nop 0
	s_nop 0
	s_nop 0
	s_nop 0
	s_nop 0
	s_nop 0
	s_nop 0
	s_nop 0
	s_nop 0
	s_nop 0
	s_nop 0
	s_nop 0
	s_nop 0
	s_nop 0
	s_nop 0
	s_nop 0
	s_nop 0
	s_nop 0
	s_nop 0
	s_nop 0
	s_nop 0
	s_nop 0
	s_nop 0
	s_nop 0
	s_nop 0
	s_nop 0
	s_nop 0
	s_nop 0
	s_nop 0
	s_nop 0
	s_nop 0
	s_nop 0
	s_nop 0
	s_nop 0
	s_nop 0
	s_nop 0
	s_nop 0
	s_nop 0
	s_nop 0
	s_nop 0
	s_nop 0
	s_nop 0
	s_nop 0
	s_nop 0
	s_nop 0
	s_nop 0
	s_nop 0
	s_nop 0
	s_nop 0
	s_nop 0
	s_nop 0
	s_nop 0
	s_nop 0
	s_nop 0
	s_nop 0
	s_nop 0
	s_nop 0
	s_nop 0
	s_nop 0
	s_nop 0
	s_nop 0
	s_nop 0
	s_nop 0
	s_nop 0
	s_nop 0
	s_nop 0
	s_nop 0
	s_nop 0
	s_nop 0
	s_nop 0
	s_nop 0
	s_nop 0
	s_nop 0
	s_nop 0
	s_nop 0
	s_nop 0
	s_nop 0
	s_nop 0
	s_nop 0
	s_nop 0
	s_nop 0
	s_nop 0
	s_nop 0
	s_nop 0
	s_nop 0
	s_nop 0
	s_nop 0
	s_nop 0
	s_nop 0
	s_nop 0
	s_nop 0
	s_nop 0
	s_nop 0
	s_nop 0
	s_nop 0
	s_nop 0
	s_nop 0
	s_nop 0
	s_nop 0
	s_nop 0
	s_nop 0
	s_nop 0
	s_nop 0
	s_nop 0
	s_nop 0
	s_nop 0
	s_nop 0
	s_nop 0
	s_nop 0
	s_nop 0
	s_nop 0
	s_nop 0
	s_nop 0
	s_nop 0
	s_nop 0
	s_nop 0
	s_nop 0
	s_nop 0
	s_nop 0
	s_nop 0
	s_nop 0
	s_nop 0
	s_nop 0
	s_nop 0
	s_nop 0
	s_nop 0
	s_nop 0
	s_nop 0
	s_nop 0
	s_nop 0
	s_nop 0
	s_nop 0
	s_nop 0
	s_nop 0
	s_nop 0
	s_nop 0
	s_nop 0
	s_nop 0
	s_nop 0
	s_nop 0
	s_nop 0
	s_nop 0
	s_nop 0
	s_nop 0
	s_nop 0
	s_nop 0
	s_nop 0
	s_nop 0
	s_nop 0
	s_nop 0
	s_nop 0
	s_nop 0
	s_nop 0
	s_nop 0
	s_nop 0
	s_nop 0
	s_nop 0
	s_nop 0
	s_nop 0
	s_nop 0
	s_nop 0
	s_nop 0
	s_nop 0
	s_nop 0
	s_nop 0
	s_nop 0
	s_nop 0
	s_nop 0
	s_nop 0
	s_nop 0
	s_nop 0
	s_nop 0
	s_nop 0
	s_nop 0
	s_nop 0
	s_nop 0
	s_nop 0
	s_nop 0
	s_nop 0
	s_nop 0
	s_nop 0
	s_nop 0
	s_nop 0
	s_nop 0
	s_nop 0
	s_nop 0
	s_nop 0
	s_nop 0
	s_nop 0
	s_nop 0
	s_nop 0
	s_nop 0
	s_nop 0
	s_nop 0
	s_nop 0
	s_nop 0
	s_nop 0
	s_nop 0
	s_nop 0
	s_nop 0
	s_nop 0
	s_nop 0
	s_nop 0
	s_nop 0
	s_nop 0
	s_nop 0
	s_nop 0
	s_nop 0
	s_nop 0
	s_nop 0
	s_nop 0
	s_nop 0
	s_nop 0
	s_nop 0
	s_nop 0
	s_nop 0
	s_nop 0
	s_nop 0
	s_nop 0
	s_nop 0
	s_nop 0
	s_nop 0
	s_nop 0
	s_nop 0
	s_nop 0
	s_nop 0
	s_nop 0
	s_nop 0
	s_nop 0
	s_nop 0
	s_nop 0
	s_nop 0
	s_nop 0
	s_nop 0
	s_nop 0
	s_nop 0
	s_nop 0
	s_nop 0
	s_nop 0
	s_nop 0
	s_nop 0
	s_nop 0
	s_nop 0
	s_nop 0
	s_nop 0
	s_nop 0
	s_nop 0
	s_nop 0
	s_nop 0
	s_nop 0
	s_nop 0
	s_nop 0
	s_nop 0
	s_nop 0
	s_nop 0
	s_nop 0
	s_nop 0
	s_nop 0
	s_nop 0
	s_nop 0
	s_nop 0
	s_nop 0
	s_nop 0
	s_nop 0
	s_nop 0
	s_nop 0
	s_nop 0
	s_nop 0
	s_nop 0
	s_nop 0
	s_nop 0
	s_nop 0
	s_nop 0
	s_nop 0
	s_nop 0
	s_nop 0
	s_nop 0
	s_nop 0
	s_nop 0
	s_nop 0
	s_nop 0
	s_nop 0
	s_nop 0
	s_nop 0
	s_nop 0
	s_nop 0
	s_nop 0
	s_nop 0
	s_nop 0
	s_nop 0
	s_nop 0
	s_nop 0
	s_nop 0
	s_nop 0
	s_nop 0
	s_nop 0
	s_nop 0
	s_nop 0
	s_nop 0
	s_nop 0
	s_nop 0
	s_nop 0
	s_nop 0
	s_nop 0
	s_nop 0
	s_nop 0
	s_nop 0
	s_nop 0
	s_nop 0
	s_nop 0
	s_nop 0
	s_nop 0
	s_nop 0
	s_nop 0
	s_nop 0
	s_nop 0
	s_nop 0
	s_nop 0
	s_nop 0
	s_nop 0
	s_nop 0
	s_nop 0
	s_nop 0
	s_nop 0
	s_nop 0
	s_nop 0
	s_nop 0
	s_nop 0
	s_nop 0
	s_nop 0
	s_nop 0
	s_nop 0
	s_nop 0
	s_nop 0
	s_nop 0
	s_nop 0
	s_nop 0
	s_nop 0
	s_nop 0
	s_nop 0
	s_nop 0
	s_nop 0
	s_nop 0
	s_nop 0
	s_nop 0
	s_nop 0
	s_nop 0
	s_nop 0
	s_nop 0
	s_nop 0
	s_nop 0
	s_nop 0
	s_nop 0
	s_nop 0
	s_nop 0
	s_nop 0
	s_nop 0
	s_nop 0
	s_nop 0
	s_nop 0
	s_nop 0
	s_nop 0
	s_nop 0
	s_nop 0
	s_nop 0
	s_nop 0
	s_nop 0
	s_nop 0
	s_nop 0
	s_nop 0
	s_nop 0
	s_nop 0
	s_nop 0
	s_nop 0
	s_nop 0
	s_nop 0
	s_nop 0
	s_nop 0
	s_nop 0
	s_nop 0
	s_nop 0
	s_nop 0
	s_nop 0
	s_nop 0
	s_nop 0
	s_nop 0
	s_nop 0
	s_nop 0
	s_nop 0
	s_nop 0
	s_nop 0
	s_nop 0
	s_nop 0
	s_nop 0
	s_nop 0
	s_nop 0
	s_nop 0
	s_nop 0
	s_nop 0
	s_nop 0
	s_nop 0
	s_nop 0
	s_nop 0
	s_nop 0
	s_nop 0
	s_nop 0
	s_nop 0
	s_nop 0
	s_nop 0
	s_nop 0
	s_nop 0
	s_nop 0
	s_nop 0
	s_nop 0
	s_nop 0
	s_nop 0
	s_nop 0
	s_nop 0
	s_nop 0
	s_nop 0
	s_nop 0
	s_nop 0
	s_nop 0
	s_nop 0
	s_nop 0
	s_nop 0
	s_nop 0
	s_nop 0
	s_nop 0
	s_nop 0
	s_nop 0
	s_nop 0
	s_nop 0
	s_nop 0
	s_nop 0
	s_nop 0
	s_nop 0
	s_nop 0
	s_nop 0
	s_nop 0
	s_nop 0
	s_nop 0
	s_nop 0
	s_nop 0
	s_nop 0
	s_nop 0
	s_nop 0
	s_nop 0
	s_nop 0
	s_nop 0
	s_nop 0
	s_nop 0
	s_nop 0
	s_nop 0
	s_nop 0
	s_nop 0
	s_nop 0
	s_nop 0
	s_nop 0
	s_nop 0
	s_nop 0
	s_nop 0
	s_nop 0
	s_nop 0
	s_nop 0
	s_nop 0
	s_nop 0
	s_nop 0
	s_nop 0
	s_nop 0
	s_nop 0
	s_nop 0
	s_nop 0
	s_nop 0
	s_nop 0
	s_nop 0
	s_nop 0
	s_nop 0
	s_nop 0
	s_nop 0
	s_nop 0
	s_nop 0
	s_nop 0
	s_nop 0
	s_nop 0
; __device__ __forceinline__ float bf2f(unsigned short h) { return __uint_as_float(((unsigned)h) << 16); }
; __device__ __forceinline__ void s5_unit(ArgsP A, int l, int unit, unsigned char* lds, int wave_, int lane_) {
;     ...
;     __syncthreads();
;     const bf16_t* WG = (const bf16_t*)(A->ws + WS_W + (size_t)l * WL_SIZE + WL_WGLU);
;     f32x4 acc[4][4];
; #pragma unroll
;     for (int mb = 0; mb < 4; ++mb)
; #pragma unroll
;         for (int nb = 0; nb < 4; ++nb) acc[mb][nb] = (f32x4){0.f, 0.f, 0.f, 0.f};
;     {
;         const bf16_t* wb = WG + (size_t)(64 * wave + (lane & 15)) * 512 + 8 * (lane >> 4);
;         bf16x8 bq[4][4];
; #pragma unroll
;         for (int p = 0; p < 4; ++p)
; #pragma unroll
;             for (int nb = 0; nb < 4; ++nb) bq[p][nb] = *(const bf16x8*)(wb + (size_t)(16 * nb) * 512 + 32 * p);
; #pragma unroll
;         for (int ks = 0; ks < 16; ++ks) {
;             bf16x8 af[4];
; #pragma unroll
;             for (int mb = 0; mb < 4; ++mb) af[mb] = *(const bf16x8*)(ys + (16 * mb + (lane & 15)) * YS_STRIDE + 32 * ks + 8 * (lane >> 4));
;             asm volatile("" : "+v"(bq[ks & 3][0]), "+v"(bq[ks & 3][1]), "+v"(bq[ks & 3][2]), "+v"(bq[ks & 3][3]) :: "memory");
; #pragma unroll
;             for (int mb = 0; mb < 4; ++mb)
; #pragma unroll
;                 for (int nb = 0; nb < 4; ++nb) acc[mb][nb] = __builtin_amdgcn_mfma_f32_16x16x32_bf16(af[mb], bq[ks & 3][nb], acc[mb][nb], 0, 0, 0);
;             if (ks + 4 < 16) {
; #pragma unroll
;                 for (int nb = 0; nb < 4; ++nb) bq[ks & 3][nb] = *(const bf16x8*)(wb + (size_t)(16 * nb) * 512 + 32 * (ks + 4));
;             }
;         }
;     }
;     bf16_t* MIX = (bf16_t*)(A->ws + WS_MIX);
;     float bglv[4];
; #pragma unroll
;     for (int nb = 0; nb < 4; ++nb) bglv[nb] = A->in[22][l * 512 + 64 * wave + 16 * nb + (lane & 15)];
; #pragma unroll
;     for (int nb = 0; nb < 4; ++nb) { const int n = 64 * wave + 16 * nb + (lane & 15); const float bgl = bglv[nb];
; #pragma unroll
;         for (int mb = 0; mb < 4; ++mb)
; #pragma unroll
;             for (int i = 0; i < 4; ++i) { const int t = 16 * mb + 4 * (lane >> 4) + i; const float yv = bf2f(ys[t * YS_STRIDE + n]);
;                 MIX[(size_t)(rowbase + t) * DM + n] = f2bf(yv * sigmoidf_(acc[mb][nb][i] + bgl)); } }
;     __syncthreads();
	s_nop 0
	s_nop 0
	s_nop 0
	s_nop 0
	s_nop 0
	s_nop 0
	s_nop 0
	s_nop 0
	s_nop 0
	s_nop 0
	s_nop 0
	s_nop 0
	s_nop 0
	s_nop 0
	s_nop 0
	s_nop 0
	s_nop 0
	s_nop 0
	s_nop 0
	s_nop 0
	s_nop 0
	s_nop 0
	s_nop 0
	s_nop 0
	s_nop 0
	s_nop 0
	s_nop 0
	s_nop 0
	s_nop 0
	s_nop 0
	s_nop 0
	s_nop 0
	s_nop 0
	s_nop 0
	s_nop 0
	s_nop 0
	s_nop 0
	s_nop 0
	s_nop 0
	s_nop 0
	s_nop 0
	s_nop 0
	s_nop 0
	s_nop 0
	s_nop 0
	s_nop 0
	s_nop 0
	s_nop 0
	s_nop 0
	s_nop 0
	s_nop 0
	s_nop 0
	s_nop 0
	s_nop 0
	s_nop 0
	s_nop 0
	s_nop 0
	s_nop 0
	s_nop 0
	s_nop 0
	s_nop 0
	s_nop 0
	s_nop 0
	s_nop 0
	s_nop 0
	s_nop 0
	s_nop 0
	s_nop 0
	s_nop 0
	s_nop 0
	s_nop 0
	s_nop 0
	s_nop 0
	s_nop 0
	s_nop 0
	s_nop 0
	s_nop 0
	s_nop 0
	s_nop 0
	s_nop 0
	s_nop 0
	s_nop 0
	s_nop 0
	s_nop 0
	s_nop 0
	s_nop 0
	s_nop 0
	s_nop 0
	s_nop 0
	s_nop 0
	s_nop 0
	s_nop 0
	s_nop 0
	s_nop 0
	s_nop 0
	s_nop 0
	s_nop 0
	s_nop 0
	s_nop 0
	s_nop 0
	s_nop 0
	s_nop 0
	s_nop 0
	s_nop 0
	s_nop 0
	s_nop 0
	s_nop 0
	s_nop 0
	s_nop 0
	s_nop 0
	s_nop 0
	s_nop 0
	s_nop 0
	s_nop 0
	s_nop 0
	s_nop 0
	s_nop 0
	s_nop 0
	s_nop 0
	s_nop 0
	s_nop 0
	s_nop 0
	s_nop 0
	s_nop 0
	s_nop 0
	s_nop 0
	s_nop 0
	s_nop 0
	s_nop 0
	s_nop 0
	s_nop 0
	s_nop 0
	s_nop 0
	s_nop 0
	s_nop 0
	s_nop 0
	s_nop 0
	s_nop 0
	s_nop 0
	s_nop 0
	s_nop 0
	s_nop 0
	s_nop 0
	s_nop 0
	s_nop 0
	s_nop 0
	s_nop 0
	s_nop 0
	s_nop 0
	s_nop 0
	s_nop 0
	s_nop 0
	s_nop 0
	s_nop 0
	s_nop 0
	s_nop 0
	s_nop 0
	s_nop 0
	s_nop 0
	s_nop 0
	s_nop 0
	s_nop 0
	s_nop 0
	s_nop 0
	s_nop 0
	s_nop 0
	s_nop 0
	s_nop 0
	s_nop 0
	s_nop 0
	s_nop 0
	s_nop 0
	s_nop 0
	s_nop 0
	s_nop 0
	s_nop 0
	s_nop 0
	s_nop 0
	s_nop 0
	s_nop 0
	s_nop 0
	s_nop 0
	s_nop 0
	s_nop 0
	s_nop 0
	s_nop 0
	s_nop 0
	s_nop 0
	s_nop 0
	s_nop 0
	s_nop 0
	s_nop 0
	s_nop 0
	s_nop 0
	s_nop 0
	s_nop 0
	s_nop 0
	s_nop 0
	s_nop 0
	s_nop 0
	s_nop 0
	s_nop 0
	s_nop 0
	s_nop 0
	s_nop 0
	s_nop 0
	s_nop 0
	s_nop 0
	s_nop 0
	s_nop 0
	s_nop 0
	s_nop 0
	s_nop 0
	s_nop 0
	s_nop 0
	s_nop 0
	s_nop 0
	s_nop 0
	s_nop 0
	s_nop 0
	s_nop 0
	s_nop 0
	s_nop 0
	s_nop 0
	s_nop 0
	s_nop 0
	s_nop 0
	s_nop 0
	s_nop 0
	s_nop 0
	s_nop 0
	s_nop 0
	s_nop 0
	s_nop 0
	s_nop 0
	s_nop 0
	s_nop 0
	s_nop 0
	s_nop 0
	s_nop 0
	s_nop 0
	s_nop 0
	s_nop 0
	s_nop 0
	s_nop 0
	s_nop 0
	s_nop 0
	s_nop 0
	s_nop 0
	s_nop 0
	s_nop 0
	s_nop 0
	s_nop 0
	s_nop 0
	s_nop 0
	s_nop 0
	s_nop 0
	s_nop 0
	s_nop 0
	s_nop 0
	s_nop 0
	s_nop 0
	s_nop 0
	s_nop 0
	s_nop 0
	s_nop 0
	s_nop 0
	s_nop 0
	s_nop 0
	s_nop 0
	s_nop 0
	s_nop 0
	s_nop 0
	s_nop 0
	s_nop 0
	s_nop 0
	s_nop 0
	s_nop 0
	s_nop 0
	s_nop 0
	s_nop 0
	s_nop 0
	s_nop 0
	s_nop 0
	s_nop 0
	s_nop 0
	s_nop 0
	s_nop 0
	s_nop 0
	s_nop 0
	s_nop 0
	s_nop 0
	s_nop 0
	s_nop 0
	s_nop 0
	s_nop 0
	s_nop 0
	s_nop 0
	s_nop 0
	s_nop 0
	s_nop 0
	s_nop 0
	s_nop 0
	s_nop 0
	s_nop 0
	s_nop 0
	s_nop 0
	s_nop 0
	s_nop 0
	s_nop 0
	s_nop 0
	s_nop 0
	s_nop 0
	s_nop 0
	s_nop 0
	s_nop 0
	s_nop 0
	s_nop 0
	s_nop 0
	s_nop 0
	s_nop 0
	s_nop 0
	s_nop 0
	s_nop 0
	s_nop 0
	s_nop 0
	s_nop 0
	s_nop 0
	s_nop 0
	s_nop 0
	s_nop 0
	s_nop 0
	s_nop 0
	s_nop 0
	s_nop 0
	s_nop 0
	s_nop 0
	s_nop 0
	s_nop 0
	s_nop 0
	s_nop 0
	s_nop 0
	s_nop 0
	s_nop 0
	s_nop 0
	s_nop 0
	s_nop 0
	s_nop 0
	s_nop 0
	s_nop 0
	s_nop 0
	s_nop 0
	s_nop 0
	s_nop 0
	s_nop 0
	s_nop 0
	s_nop 0
	s_nop 0
	s_nop 0
	s_nop 0
	s_nop 0
	s_nop 0
	s_nop 0
	s_nop 0
	s_nop 0
	s_nop 0
	s_nop 0
	s_nop 0
	s_nop 0
	s_nop 0
	s_nop 0
	s_nop 0
	s_nop 0
	s_nop 0
	s_nop 0
	s_nop 0
	s_nop 0
	s_nop 0
	s_nop 0
	s_nop 0
	s_nop 0
	s_nop 0
	s_nop 0
	s_nop 0
	s_nop 0
	s_nop 0
	s_nop 0
	s_nop 0
	s_nop 0
	s_nop 0
	s_nop 0
	s_nop 0
	s_nop 0
	s_nop 0
	s_nop 0
	s_nop 0
	s_nop 0
	s_nop 0
	s_nop 0
	s_nop 0
	s_nop 0
	s_nop 0
	s_nop 0
	s_nop 0
	s_nop 0
	s_nop 0
	s_nop 0
	s_nop 0
	s_nop 0
	s_nop 0
	s_nop 0
	s_nop 0
	s_nop 0
	s_nop 0
	s_nop 0
	s_nop 0
	s_nop 0
	s_nop 0
	s_nop 0
	s_nop 0
	s_nop 0
	s_nop 0
	s_nop 0
	s_nop 0
	s_nop 0
	s_nop 0
	s_nop 0
	s_nop 0
	s_nop 0
	s_nop 0
	s_nop 0
	s_nop 0
	s_nop 0
	s_nop 0
	s_nop 0
	s_nop 0
	s_nop 0
	s_nop 0
	s_nop 0
	s_nop 0
	s_nop 0
	s_nop 0
	s_nop 0
	s_nop 0
	s_nop 0
	s_nop 0
	s_nop 0
	s_nop 0
	s_nop 0
	s_nop 0
	s_nop 0
	s_nop 0
	s_nop 0
	s_nop 0
	s_nop 0
	s_nop 0
	s_nop 0
	s_nop 0
	s_nop 0
	s_nop 0
	s_nop 0
	s_nop 0
	s_nop 0
	s_nop 0
	s_nop 0
	s_nop 0
	s_nop 0
	s_nop 0
	s_nop 0
	s_nop 0
	s_nop 0
	s_nop 0
	s_nop 0
	s_nop 0
	s_nop 0
	s_nop 0
	s_nop 0
	s_nop 0
	s_nop 0
	s_nop 0
	s_nop 0
	s_nop 0
	s_nop 0
	s_nop 0
	s_nop 0
	s_nop 0
	s_nop 0
	s_nop 0
	s_nop 0
	s_nop 0
	s_nop 0
	s_nop 0
	s_nop 0
	s_nop 0
	s_nop 0
	s_nop 0
	s_nop 0
	s_nop 0
	s_nop 0
	s_nop 0
	s_nop 0
	s_nop 0
	s_nop 0
	s_nop 0
	s_nop 0
	s_nop 0
	s_nop 0
	s_nop 0
	s_nop 0
	s_nop 0
	s_nop 0
	s_nop 0
	s_nop 0
	s_nop 0
	s_nop 0
	s_nop 0
	s_nop 0
	s_nop 0
	s_nop 0
	s_nop 0
	s_nop 0
	s_nop 0
	s_nop 0
	s_nop 0
	s_nop 0
	s_nop 0
	s_nop 0
	s_nop 0
	s_nop 0
	s_nop 0
	s_nop 0
	s_nop 0
	s_nop 0
	s_nop 0
	s_nop 0
	s_nop 0
	s_nop 0
	s_nop 0
	s_nop 0
	s_nop 0
	s_nop 0
	s_nop 0
	s_nop 0
	s_nop 0
	s_nop 0
	s_nop 0
	s_nop 0
	s_nop 0
	s_nop 0
	s_nop 0
	s_nop 0
	s_nop 0
	s_nop 0
	s_nop 0
	s_nop 0
	s_nop 0
	s_nop 0
	s_nop 0
	s_nop 0
	s_nop 0
	s_nop 0
	s_nop 0
	s_nop 0
	s_nop 0
	s_nop 0
	s_nop 0
	s_nop 0
	s_nop 0
	s_nop 0
	s_nop 0
	s_nop 0
	s_nop 0
	s_nop 0
	s_nop 0
	s_nop 0
	s_nop 0
	s_nop 0
	s_nop 0
	s_nop 0
	s_nop 0
	s_nop 0
	s_nop 0
	s_nop 0
	s_nop 0
	s_nop 0
	s_nop 0
	s_nop 0
	s_nop 0
	s_nop 0
	s_nop 0
	s_nop 0
	s_nop 0
	s_nop 0
	s_nop 0
	s_nop 0
	s_nop 0
	s_nop 0
	s_nop 0
	s_nop 0
	s_nop 0
	s_nop 0
	s_nop 0
	s_nop 0
	s_nop 0
	s_nop 0
	s_nop 0
	s_nop 0
	s_nop 0
	s_nop 0
	s_nop 0
